# rec_pass1 chunk-local state: MFMA operands exchanged (transposed accumulators) so each lane stores 16-B write-through pieces instead of 16/8 scattered dwords
# speedup vs baseline: 1.0046x; 1.0046x over previous
.LBB0_197:
	v_add_u32_e32 v7, 0x4400, v6
	ds_read2_b32 v[8:9], v7 offset1:33
	ds_read2_b32 v[10:11], v6 offset1:33
	v_add_u32_e32 v13, s2, v5
	s_add_i32 s2, s2, 8
	s_cmp_eq_u32 s2, 16
	s_waitcnt lgkmcnt(0)
	v_sub_f32_e32 v10, v4, v10
	v_mul_f32_e32 v10, 0x3fb8aa3b, v10
	v_exp_f32_e32 v10, v10
	s_nop 0
	v_mul_f32_e32 v12, v8, v10
	v_sub_f32_e32 v8, v4, v11
	v_mul_f32_e32 v8, 0x3fb8aa3b, v8
	v_exp_f32_e32 v8, v8
	s_nop 0
	v_mul_f32_e32 v14, v9, v8
	ds_read2_b32 v[8:9], v7 offset0:66 offset1:99
	ds_read2_b32 v[10:11], v6 offset0:66 offset1:99
	v_add_u32_e32 v6, 0x210, v6
	s_waitcnt lgkmcnt(0)
	v_sub_f32_e32 v7, v4, v10
	v_mul_f32_e32 v7, 0x3fb8aa3b, v7
	v_exp_f32_e32 v7, v7
	s_nop 0
	v_mul_f32_e32 v7, v8, v7
	v_sub_f32_e32 v8, v4, v11
	v_mul_f32_e32 v8, 0x3fb8aa3b, v8
	v_exp_f32_e32 v8, v8
	s_nop 0
	v_mul_f32_e32 v8, v9, v8
	v_cvt_pk_bf16_f32 v9, v7, v8
	v_cvt_pk_bf16_f32 v8, v12, v14
	ds_write_b64 v13, v[8:9]
	s_cbranch_scc0 .LBB0_197
	v_lshl_add_u32 v8, v15, 1, v105
	s_movk_i32 s2, 0x90
	v_mad_u32_u24 v12, v110, s2, v8
	s_waitcnt lgkmcnt(0)
	s_barrier
	ds_read_b128 v[4:7], v12 offset:34816
	v_mad_u32_u24 v13, v107, s2, v8
	ds_read_b128 v[8:11], v13 offset:44032
	ds_read_b128 v[16:19], v13 offset:46336
	ds_read_b128 v[20:23], v12 offset:34880
	ds_read_b128 v[24:27], v13 offset:46400
	s_waitcnt lgkmcnt(3)
	v_mfma_f32_16x16x32_bf16 v[8:11], v[8:11], v[4:7], 0
	v_ashrrev_i32_e32 v103, 31, v102
	v_readlane_b32 s2, v254, 17
	v_readlane_b32 s3, v254, 18
	s_waitcnt lgkmcnt(2)
	v_mfma_f32_16x16x32_bf16 v[4:7], v[16:19], v[4:7], 0
	ds_read_b128 v[16:19], v13 offset:44096
	v_mov_b32_e32 v13, v177
	v_cmp_lt_u32_sdwa s[4:5], v111, v218 src0_sel:BYTE_0 src1_sel:DWORD
	s_waitcnt lgkmcnt(1)
	v_mfma_f32_16x16x32_bf16 v[4:7], v[24:27], v[20:23], v[4:7]
	v_lshlrev_b32_e32 v24, 2, v112
	s_waitcnt lgkmcnt(0)
	v_mfma_f32_16x16x32_bf16 v[16:19], v[16:19], v[20:23], v[8:11]
	s_nop 2
	v_or_b32_e32 v198, v113, v107
	v_lshl_or_b32 v198, v198, 5, v24
	v_lshlrev_b32_e32 v196, 2, v198
	v_mov_b32_e32 v197, v177
	v_or_b32_e32 v11, v113, v24
	v_lshlrev_b32_e32 v11, 5, v11
	v_lshlrev_b64 v[8:9], 13, v[102:103]
	v_or_b32_e32 v12, v11, v107
	v_lshl_add_u64 v[8:9], s[2:3], 0, v[8:9]
	v_lshl_add_u64 v[196:197], v[8:9], 0, v[196:197]
	v_lshlrev_b32_e32 v12, 2, v12
	v_or_b32_e32 v10, 16, v107
	v_lshl_add_u64 v[12:13], v[8:9], 0, v[12:13]
	global_store_dwordx4 v[196:197], v[16:19], off sc1
	global_store_dwordx4 v[196:197], v[4:7], off offset:64 sc1
	s_nop 1
	v_or_b32_e32 v4, v11, v10
	v_lshlrev_b32_e32 v12, 2, v4
	v_mov_b32_e32 v13, v177
	v_lshl_add_u64 v[8:9], v[8:9], 0, v[12:13]
	s_and_saveexec_b64 s[2:3], s[4:5]
	s_cbranch_execz .LBB0_200
	v_lshlrev_b32_sdwa v4, v213, v111 dst_sel:DWORD dst_unused:UNUSED_PAD src0_sel:DWORD src1_sel:BYTE_0
	v_add_u32_e32 v5, v105, v4
	ds_read_b32 v5, v5 offset:8316
	v_readlane_b32 s4, v254, 19
	v_lshlrev_b64 v[6:7], 7, v[102:103]
	v_readlane_b32 s5, v254, 20
	s_waitcnt lgkmcnt(0)
	v_mul_f32_e32 v5, 0x3fb8aa3b, v5
	v_exp_f32_e32 v8, v5
	v_lshl_add_u64 v[6:7], s[4:5], 0, v[6:7]
	v_mov_b32_e32 v5, v177
	v_lshl_add_u64 v[4:5], v[6:7], 0, v[4:5]
	global_store_dword v[4:5], v8, off

.LBB0_241:
	v_add_u32_e32 v11, 0x4400, v10
	ds_read2_b32 v[12:13], v11 offset1:65
	ds_read2_b32 v[14:15], v10 offset1:65
	v_add_u32_e32 v18, s2, v9
	s_add_i32 s2, s2, 8
	s_cmp_eq_u32 s2, 32
	s_waitcnt lgkmcnt(0)
	v_sub_f32_e32 v14, v8, v14
	v_mul_f32_e32 v14, 0x3fb8aa3b, v14
	v_exp_f32_e32 v14, v14
	s_nop 0
	v_mul_f32_e32 v17, v12, v14
	v_sub_f32_e32 v12, v8, v15
	v_mul_f32_e32 v12, 0x3fb8aa3b, v12
	v_exp_f32_e32 v12, v12
	s_nop 0
	v_mul_f32_e32 v20, v13, v12
	ds_read2_b32 v[12:13], v11 offset0:130 offset1:195
	ds_read2_b32 v[14:15], v10 offset0:130 offset1:195
	v_add_u32_e32 v10, 0x410, v10
	s_waitcnt lgkmcnt(0)
	v_sub_f32_e32 v11, v8, v14
	v_mul_f32_e32 v11, 0x3fb8aa3b, v11
	v_exp_f32_e32 v11, v11
	s_nop 0
	v_mul_f32_e32 v11, v12, v11
	v_sub_f32_e32 v12, v8, v15
	v_mul_f32_e32 v12, 0x3fb8aa3b, v12
	v_exp_f32_e32 v12, v12
	s_nop 0
	v_mul_f32_e32 v12, v13, v12
	v_cvt_pk_bf16_f32 v13, v11, v12
	v_cvt_pk_bf16_f32 v12, v17, v20
	ds_write_b64 v18, v[12:13]
	s_cbranch_scc0 .LBB0_241
	v_lshl_add_u32 v12, v29, 1, v28
	s_movk_i32 s2, 0x90
	v_mad_u32_u24 v17, v19, s2, v12
	s_waitcnt lgkmcnt(0)
	s_barrier
	ds_read_b128 v[8:11], v17 offset:34816
	v_mad_u32_u24 v18, v26, s2, v12
	ds_read_b128 v[12:15], v18 offset:44032
	ds_read_b128 v[34:37], v18 offset:46336
	ds_read_b128 v[38:41], v18 offset:48640
	ds_read_b128 v[42:45], v18 offset:50944
	s_waitcnt lgkmcnt(3)
	v_mfma_f32_16x16x32_bf16 v[12:15], v[12:15], v[8:11], 0
	v_lshlrev_b32_e32 v30, 2, v23
	v_mov_b32_e32 v33, v177
	v_or_b32_e32 v51, 16, v26
	s_waitcnt lgkmcnt(2)
	v_mfma_f32_16x16x32_bf16 v[34:37], v[34:37], v[8:11], 0
	v_or_b32_e32 v48, 32, v26
	v_or_b32_e32 v31, 48, v26
	v_cmp_lt_u32_sdwa s[4:5], v22, v216 src0_sel:BYTE_0 src1_sel:DWORD
	s_waitcnt lgkmcnt(1)
	v_mfma_f32_16x16x32_bf16 v[38:41], v[38:41], v[8:11], 0
	s_waitcnt lgkmcnt(0)
	v_mfma_f32_16x16x32_bf16 v[8:11], v[42:45], v[8:11], 0
	ds_read_b128 v[42:45], v17 offset:34880
	ds_read_b128 v[52:55], v18 offset:44096
	v_ashrrev_i32_e32 v17, 31, v16
	v_lshlrev_b64 v[20:21], 14, v[16:17]
	s_waitcnt lgkmcnt(0)
	v_mfma_f32_16x16x32_bf16 v[12:15], v[52:55], v[42:45], v[12:15]
	ds_read_b128 v[52:55], v18 offset:46400
	v_lshl_add_u64 v[20:21], s[78:79], 0, v[20:21]
	s_waitcnt lgkmcnt(0)
	v_mfma_f32_16x16x32_bf16 v[34:37], v[52:55], v[42:45], v[34:37]
	ds_read_b128 v[52:55], v18 offset:48704
	s_waitcnt lgkmcnt(0)
	v_mfma_f32_16x16x32_bf16 v[38:41], v[52:55], v[42:45], v[38:41]
	ds_read_b128 v[52:55], v18 offset:51008
	v_or_b32_e32 v66, v32, v26
	v_lshl_or_b32 v66, v66, 6, v30
	v_lshlrev_b32_e32 v66, 2, v66
	v_mov_b32_e32 v67, v177
	v_lshl_add_u64 v[66:67], v[20:21], 0, v[66:67]
	v_or_b32_e32 v18, v32, v30
	v_lshlrev_b32_e32 v18, 6, v18
	v_or_b32_e32 v23, v18, v26
	v_lshlrev_b32_e32 v32, 2, v23
	v_lshl_add_u64 v[32:33], v[20:21], 0, v[32:33]
	global_store_dwordx4 v[66:67], v[12:15], off sc1
	global_store_dwordx4 v[66:67], v[34:37], off offset:64 sc1
	global_store_dwordx4 v[66:67], v[38:41], off offset:128 sc1
	s_nop 1
	v_or_b32_e32 v12, v18, v51
	v_lshlrev_b32_e32 v12, 2, v12
	v_mov_b32_e32 v13, v177
	v_lshl_add_u64 v[12:13], v[20:21], 0, v[12:13]
	v_or_b32_e32 v12, v18, v48
	v_lshlrev_b32_e32 v12, 2, v12
	v_mov_b32_e32 v13, v177
	s_waitcnt lgkmcnt(0)
	v_mfma_f32_16x16x32_bf16 v[8:11], v[52:55], v[42:45], v[8:11]
	v_lshl_add_u64 v[12:13], v[20:21], 0, v[12:13]
	s_nop 3
	s_nop 3
	global_store_dwordx4 v[66:67], v[8:11], off offset:192 sc1
	s_nop 1
	v_or_b32_e32 v8, v18, v31
	v_lshlrev_b32_e32 v12, 2, v8
	v_mov_b32_e32 v13, v177
	v_lshl_add_u64 v[12:13], v[20:21], 0, v[12:13]
	s_and_saveexec_b64 s[2:3], s[4:5]
	s_cbranch_execz .LBB0_244
	v_lshlrev_b32_sdwa v8, v213, v22 dst_sel:DWORD dst_unused:UNUSED_PAD src0_sel:DWORD src1_sel:BYTE_0
	v_add_u32_e32 v9, v28, v8
	ds_read_b32 v9, v9 offset:16380
	v_readlane_b32 s4, v254, 21
	v_lshlrev_b64 v[10:11], 8, v[16:17]
	v_readlane_b32 s5, v254, 22
	s_waitcnt lgkmcnt(0)
	v_mul_f32_e32 v9, 0x3fb8aa3b, v9
	v_exp_f32_e32 v12, v9
	v_lshl_add_u64 v[10:11], s[4:5], 0, v[10:11]
	v_mov_b32_e32 v9, v177
	v_lshl_add_u64 v[8:9], v[10:11], 0, v[8:9]
	global_store_dword v[8:9], v12, off
